# grid barrier: acquire L1 invalidate issued right after the release write-back so it overlaps the arrival atomics and the spin (on v20)
# speedup vs baseline: 1.0067x; 1.0026x over previous
; DI unsigned bar_ld(unsigned* p) { return __hip_atomic_load(p, __ATOMIC_RELAXED, __HIP_MEMORY_SCOPE_AGENT); }
; DI void fast_grid_sync(unsigned* bar, const unsigned k, const unsigned nb, const unsigned bid, int tid) {
;     ...
;     if (!last) while (bar_ld(bar + 64 * 16) < k * 8u && ++spins < (1u << 22)) __builtin_amdgcn_s_sleep(1);
;     __builtin_amdgcn_fence(__ATOMIC_ACQUIRE, "agent");
;     asm volatile("s_waitcnt vmcnt(0)" ::: "memory");
;   }
;   __syncthreads();
; __global__ void __launch_bounds__(NTHREADS) fwd_kernel(Params p, int ph0, int ph1) {
;   if (ph1 < 0) cg::this_grid().sync();
;   const int widx = __builtin_amdgcn_readfirstlane((int)(threadIdx.x >> 6));
;   unsigned nbar = 0;
;   for (int pi = ph0; pi < ph1; ++pi) {
;     int ph = pi, rep = 0;
;     if (N_PROBE > 0 && pi >= N_PHASES) { ph = (pi == N_PHASES) ? PROBE_A : PROBE_B; rep = 1; }
;     int tid;
;     asm volatile("v_mbcnt_lo_u32_b32 %0, -1, 0\n\tv_mbcnt_hi_u32_b32 %0, -1, %0\n\tv_lshl_add_u32 %0, %1, 6, %0" : "=&v"(tid) : "s"(widx));
;     int bid_ = blockIdx.x, nb_ = gridDim.x;
;     asm volatile("" : "+s"(bid_), "+s"(nb_));
;     run_phase(p, ph, tid, rep, bid_, nb_);
.LBB0_15:
	s_lshr_b32 s34, s2, 6
	s_add_u32 s0, s0, 0xa8
	s_addc_u32 s1, s1, 0
	s_add_u32 s76, s74, 0x4720000
	s_addc_u32 s77, s75, 0
	s_add_u32 s78, s74, 0x27520000
	s_addc_u32 s79, s75, 0
	s_add_u32 s80, s74, 0x1c920000
	s_addc_u32 s81, s75, 0
	s_add_u32 s82, s74, 0x24920000
	s_addc_u32 s83, s75, 0
	v_writelane_b32 v254, s0, 32
	s_cmp_lg_u64 s[68:69], 0
	v_mov_b32_e32 v1, 0
	v_writelane_b32 v254, s1, 33
	s_cselect_b64 s[0:1], -1, 0
	s_add_u32 s86, s74, 0x20920000
	s_addc_u32 s87, s75, 0
	s_add_u32 s88, s74, 0x3b00000
	s_addc_u32 s89, s75, 0
	s_add_u32 s90, s74, 0x2000000
	s_addc_u32 s91, s75, 0
	s_add_u32 s92, s74, 0x3100000
	s_addc_u32 s93, s75, 0
	s_add_u32 s94, s74, 0x3300000
	s_addc_u32 s95, s75, 0
	s_add_u32 s96, s74, 0x2c2e0000
	v_writelane_b32 v254, s0, 34
	s_addc_u32 s97, s75, 0
	v_mov_b32_e32 v240, 0x358637bd
	v_writelane_b32 v254, s1, 35
	s_add_u32 s0, s74, 0x2b920000
	s_addc_u32 s1, s75, 0
	v_writelane_b32 v254, s0, 36
	v_mbcnt_lo_u32_b32 v226, -1, 0
	v_mov_b32_e32 v229, 0x3e8
	v_writelane_b32 v254, s1, 37
	s_add_u32 s0, s74, 0x28920000
	s_addc_u32 s1, s75, 0
	v_writelane_b32 v254, s0, 38
	v_mov_b32_e32 v230, 0xfffffc18
	v_mov_b32_e32 v232, 0xfff00000
	v_writelane_b32 v254, s1, 39
	s_add_u32 s0, s74, 0x2c1e0000
	s_addc_u32 s1, s75, 0
	v_writelane_b32 v254, s0, 40
	v_mov_b32_e32 v233, 0xf149f2ca
	v_mov_b32_e32 v234, 0x3e0293ee
	v_writelane_b32 v254, s1, 41
	s_add_u32 s0, s74, 0x2c260000
	s_addc_u32 s1, s75, 0
	v_writelane_b32 v254, s0, 42
	v_mov_b32_e32 v235, 0x7f800000
	s_movk_i32 s35, 0x1000
	v_writelane_b32 v254, s1, 43
	s_add_u32 s0, s74, 0x2b9e0000
	s_addc_u32 s1, s75, 0
	v_writelane_b32 v254, s0, 44
	s_mov_b32 s42, 0x800000
	s_movk_i32 s36, 0x3fff
	v_writelane_b32 v254, s1, 45
	s_movk_i32 s37, 0x6080
	v_readlane_b32 s52, v254, 16
	v_readlane_b32 s56, v254, 20
	v_readlane_b32 s57, v254, 21
	s_cmp_lg_u64 s[56:57], 0
	v_readlane_b32 s58, v254, 22
	v_readlane_b32 s59, v254, 23
	s_cselect_b64 s[0:1], -1, 0
	v_readlane_b32 s53, v254, 17
	v_readlane_b32 s54, v254, 18
	v_readlane_b32 s55, v254, 19
	v_readlane_b32 s60, v254, 24
	v_readlane_b32 s61, v254, 25
	v_readlane_b32 s62, v254, 26
	v_readlane_b32 s63, v254, 27
	v_readlane_b32 s64, v254, 28
	v_readlane_b32 s65, v254, 29
	v_readlane_b32 s66, v254, 30
	v_readlane_b32 s67, v254, 31
	v_writelane_b32 v254, s0, 46
	s_cmp_lg_u64 s[58:59], 0
	s_movk_i32 s38, 0x110
	v_writelane_b32 v254, s1, 47
	s_cselect_b64 s[0:1], -1, 0
	v_writelane_b32 v254, s0, 48
	s_cmp_lg_u64 s[60:61], 0
	s_mov_b32 s43, 0xf149f2ca
	v_writelane_b32 v254, s1, 49
	s_cselect_b64 s[0:1], -1, 0
	v_writelane_b32 v254, s0, 50
	s_movk_i32 s50, 0x1c1
	s_mov_b32 s51, 0x3db504f3
	v_writelane_b32 v254, s1, 51
	s_add_u32 s0, s74, 0x4700000
	s_addc_u32 s1, s75, 0
	v_writelane_b32 v254, s0, 52
	s_mov_b32 s40, 0xefa18f08
	s_mov_b32 s39, 0x3f200000
	v_writelane_b32 v254, s1, 53
	s_mov_b32 s33, 0x42b17218
	v_readlane_b32 s0, v254, 0
	v_readlane_b32 s14, v254, 14
	v_readlane_b32 s15, v254, 15
	v_readlane_b32 s1, v254, 1
	s_cmp_lg_u64 s[14:15], 0
	s_cselect_b64 s[0:1], -1, 0
	v_readlane_b32 s2, v254, 2
	v_readlane_b32 s3, v254, 3
	v_readlane_b32 s4, v254, 4
	v_readlane_b32 s5, v254, 5
	v_readlane_b32 s6, v254, 6
	v_readlane_b32 s7, v254, 7
	v_readlane_b32 s8, v254, 8
	v_readlane_b32 s9, v254, 9
	v_readlane_b32 s10, v254, 10
	v_readlane_b32 s11, v254, 11
	v_readlane_b32 s12, v254, 12
	v_readlane_b32 s13, v254, 13
	v_writelane_b32 v254, s0, 54
	s_brev_b32 s41, -2
	s_mov_b64 s[26:27], 0x4000
	v_writelane_b32 v254, s1, 55
	s_add_u32 s0, s74, 0x4710000
	s_addc_u32 s1, s75, 0
	v_writelane_b32 v254, s0, 56
	s_cmp_lg_u64 s[54:55], 0
	s_mov_b32 s44, 0x3e0293ee
	v_writelane_b32 v254, s1, 57
	s_cselect_b64 s[0:1], -1, 0
	v_writelane_b32 v254, s0, 58
	s_mov_b32 s28, 0
	s_nop 0
	v_writelane_b32 v254, s1, 59
	s_lshl_b32 s0, s25, 8
	s_and_b32 s0, s0, 0x700
	s_add_u32 s0, s74, s0
	s_addc_u32 s1, s75, 0
	s_add_u32 s0, s0, 0x2e2e0000
	s_addc_u32 s1, s1, 0
	s_add_u32 s46, s74, 0x2e2e1000
	v_writelane_b32 v254, s0, 60
	s_addc_u32 s47, s75, 0
	s_nop 0
	v_writelane_b32 v254, s1, 61
	s_add_u32 s0, s72, 0x1000
	s_addc_u32 s1, s73, 0
	v_writelane_b32 v254, s0, 62
	s_nop 1
	v_writelane_b32 v254, s1, 63
	s_add_u32 s0, s74, 0x3c00
	s_addc_u32 s1, s75, 0
	v_writelane_b32 v255, s0, 0
	s_nop 1
	v_writelane_b32 v255, s1, 1
	s_add_u32 s0, s74, 0x4300000
	s_addc_u32 s1, s75, 0
	v_writelane_b32 v255, s0, 2
	s_nop 1
	v_writelane_b32 v255, s1, 3
	s_add_u32 s0, s74, 0x4500000
	s_addc_u32 s1, s75, 0
	v_writelane_b32 v255, s0, 4
	s_nop 1
	v_writelane_b32 v255, s1, 5
	s_mov_b32 s0, 0
	v_writelane_b32 v255, s0, 6
	v_writelane_b32 v255, s46, 7
	s_nop 1
	v_writelane_b32 v255, s47, 8
	s_branch .LBB0_19
.LBB0_16:
	s_or_b64 exec, exec, s[2:3]
	s_waitcnt vmcnt(0)
.LBB0_17:
	s_or_b64 exec, exec, s[0:1]
	s_mov_b64 s[0:1], 0
	s_barrier

; DI unsigned bar_add(unsigned* p) { return __hip_atomic_fetch_add(p, 1u, __ATOMIC_RELAXED, __HIP_MEMORY_SCOPE_AGENT); }
; DI void fast_grid_sync(unsigned* bar, const unsigned k, const unsigned nb, const unsigned bid, int tid) {
;   asm volatile("s_waitcnt vmcnt(0) lgkmcnt(0)" ::: "memory");
;   __syncthreads();
;   if (tid == 0) {
;     __builtin_amdgcn_fence(__ATOMIC_RELEASE, "agent");
;     asm volatile("s_waitcnt vmcnt(0)" ::: "memory");
;     const unsigned g = bid & 7u, gsz = nb >> 3;
;     unsigned spins = 0;
;     const unsigned old = bar_add(bar + 64 * g);
;     bool last = false;
;     if (old + 1u == k * gsz) last = (bar_add(bar + 64 * 16) + 1u == k * 8u);
.LBB0_911:
	s_mov_b64 s[2:3], exec
	buffer_wbl2 sc1
	s_waitcnt vmcnt(0)
	buffer_inv sc1
	v_mbcnt_lo_u32_b32 v0, s2, 0
	v_mbcnt_hi_u32_b32 v0, s3, v0
	v_cmp_eq_u32_e32 vcc, 0, v0
	s_and_saveexec_b64 s[4:5], vcc
	s_cbranch_execz .LBB0_913
	s_bcnt1_i32_b64 s2, s[2:3]
	v_mov_b32_e32 v2, s2
	v_readlane_b32 s2, v254, 60
	v_readlane_b32 s3, v254, 61
	s_nop 4
	global_atomic_add v2, v1, v2, s[2:3] sc0
